# hyena staging section batched (all conv input loads issued up front, scalar FMA chain kept in original order); s5tab: B/C parameter loads batched into wide loads, KT inner loop uses fewer packed ops
# speedup vs baseline: 1.0900x; 1.0073x over previous
; __device__ __forceinline__ int opaque_tid() { int t = threadIdx.x; asm volatile("" : "+v"(t)); return t; }
; #define layer launder_s(layer_)
; __device__ __forceinline__ void s5_disc(const Params& p, int layer, int dir, int g, int pp, float& are, float& aim, float& fre, float& fim) {
;   int idx = ((layer * 2 + dir) * 32 + g) * 64 + pp;
;   float lre = p.in[9][idx], lim = p.in[10][idx];
;   float dt = expf(p.in[11][(layer * 2 + dir) * 32 + g]);
;   float mag = expf(lre * dt);
;   float sn, cs; sincosf(lim * dt, &sn, &cs);
;   are = mag * cs; aim = mag * sn;
;   float den = lre * lre + lim * lim;
;   fre = ((are - 1.0f) * lre + aim * lim) / den;
;   fim = (aim * lre - (are - 1.0f) * lim) / den;
; }
; __device__ __forceinline__ void s5tab_item(const Params& p, int layer, int item, unsigned char* smem) {
;   int tid = opaque_tid();
;   int g = item >> 2, sub = item & 3;
;   float2* AP = (float2*)smem;
;   float2* BB = AP + 2 * 33 * 64;
;   float2* CC = BB + 2 * 64 * 16;
;   float* KT = (float*)(CC + 2 * 16 * 64);
;   if (tid < 128) {
;     int dir = tid >> 6, pp = tid & 63;
;     float are, aim, fre, fim;
;     s5_disc(p, layer, dir, g, pp, are, aim, fre, fim);
;     float pr = 1.f, pi = 0.f;
;     for (int j = 0; j <= 32; j++) {
;       AP[(dir * 33 + j) * 64 + pp] = make_float2(pr, pi);
;       float nr = pr * are - pi * aim, ni = pr * aim + pi * are; pr = nr; pi = ni;
;     }
.LBB0_85:
	s_andn2_saveexec_b64 s[4:5], s[38:39]
	v_mul_f32_e64 v4, |v3|, s51
	v_rndne_f32_e32 v14, v4
	v_cvt_i32_f32_e32 v13, v14
	v_fma_f32 v4, v14, s52, |v3|
	v_fmac_f32_e32 v4, 0xb3a22168, v14
	v_fmac_f32_e32 v4, 0xa7c234c4, v14
	s_or_b64 exec, exec, s[4:5]
	v_mul_f32_e32 v12, v8, v12
	v_mul_f32_e32 v14, 0x3fb8aa3b, v12
	v_fma_f32 v15, v12, s60, -v14
	v_rndne_f32_e32 v16, v14
	v_fmac_f32_e32 v15, 0x32a5705f, v12
	v_sub_f32_e32 v14, v14, v16
	v_add_f32_e32 v14, v14, v15
	v_cvt_i32_f32_e32 v15, v16
	v_exp_f32_e32 v14, v14
	v_cmp_ngt_f32_e32 vcc, s61, v12
	v_xor_b32_e32 v7, v7, v3
	v_mul_lo_u32 v1, v1, s63
	v_ldexp_f32 v14, v14, v15
	v_cndmask_b32_e32 v14, 0, v14, vcc
	v_cmp_nlt_f32_e32 vcc, s62, v12
	v_lshlrev_b64 v[10:11], 6, v[10:11]
	s_nop 0
	v_cndmask_b32_e32 v12, v28, v14, vcc
	v_mul_f32_e32 v14, v4, v4
	v_fmamk_f32 v15, v14, 0xb94c1982, v18
	v_fmaak_f32 v15, v14, v15, 0xbe2aaa9d
	v_mul_f32_e32 v15, v14, v15
	v_fmac_f32_e32 v4, v4, v15
	v_fmamk_f32 v15, v14, 0x37d75334, v19
	v_fmaak_f32 v15, v14, v15, 0x3d2aabf7
	v_fmaak_f32 v15, v14, v15, 0xbf000004
	v_fma_f32 v14, v14, v15, 1.0
	v_lshlrev_b32_e32 v15, 30, v13
	v_and_b32_e32 v13, 1, v13
	v_cmp_eq_u32_e32 vcc, 0, v13
	v_and_b32_e32 v15, 0x80000000, v15
	s_nop 0
	v_cndmask_b32_e32 v13, v14, v4, vcc
	v_xor_b32_e32 v4, 0x80000000, v4
	v_xor_b32_e32 v13, v7, v13
	v_cndmask_b32_e32 v4, v4, v14, vcc
	v_xor_b32_e32 v13, v13, v15
	v_xor_b32_e32 v4, v4, v15
	v_cmp_class_f32_e64 vcc, v3, s54
	v_lshlrev_b32_e32 v7, 3, v2
	v_add3_u32 v1, 0, v7, v1
	v_cndmask_b32_e32 v15, v26, v13, vcc
	v_cndmask_b32_e32 v14, v26, v4, vcc
	v_pk_mul_f32 v[30:31], v[12:13], v[14:15] op_sel_hi:[0,1]
	v_pk_mul_f32 v[16:17], v[30:31], 0 op_sel_hi:[1,0]
	v_mov_b32_e32 v7, v5
	v_pk_fma_f32 v[32:33], v[12:13], v[14:15], v[16:17] op_sel:[0,0,1] op_sel_hi:[0,1,0] neg_lo:[0,0,1] neg_hi:[0,0,1]
	v_pk_fma_f32 v[12:13], v[12:13], v[14:15], v[16:17] op_sel:[0,0,1] op_sel_hi:[0,1,0]
	v_mov_b32_e32 v12, v32
	v_pk_mul_f32 v[14:15], v[30:31], v[12:13] op_sel:[1,0]
	ds_write2st64_b64 v1, v[6:7], v[12:13] offset1:1
	v_pk_fma_f32 v[16:17], v[30:31], v[32:33], v[14:15] op_sel:[0,0,1] op_sel_hi:[1,1,0] neg_lo:[0,0,1] neg_hi:[0,0,1]
	v_pk_fma_f32 v[12:13], v[30:31], v[12:13], v[14:15] op_sel:[0,0,1] op_sel_hi:[0,1,0]
	v_mov_b32_e32 v17, v13
	v_pk_mul_f32 v[12:13], v[30:31], v[16:17] op_sel:[1,0]
	v_add_f32_e32 v34, -1.0, v30
	v_pk_fma_f32 v[14:15], v[30:31], v[16:17], v[12:13] op_sel:[0,0,1] op_sel_hi:[0,1,0] neg_lo:[0,0,1] neg_hi:[0,0,1]
	v_pk_fma_f32 v[12:13], v[30:31], v[16:17], v[12:13] op_sel:[0,0,1] op_sel_hi:[0,1,0]
	v_mov_b32_e32 v12, v14
	ds_write2st64_b64 v1, v[16:17], v[12:13] offset0:2 offset1:3
	v_pk_mul_f32 v[16:17], v[30:31], v[12:13] op_sel:[1,0]
	v_mov_b32_e32 v35, v31
	v_pk_fma_f32 v[14:15], v[30:31], v[14:15], v[16:17] op_sel:[0,0,1] op_sel_hi:[1,1,0] neg_lo:[0,0,1] neg_hi:[0,0,1]
	v_pk_fma_f32 v[12:13], v[30:31], v[12:13], v[16:17] op_sel:[0,0,1] op_sel_hi:[0,1,0]
	v_mov_b32_e32 v15, v13
	v_pk_mul_f32 v[12:13], v[30:31], v[14:15] op_sel:[1,0]
	v_mov_b32_e32 v32, v9
	v_pk_fma_f32 v[16:17], v[30:31], v[14:15], v[12:13] op_sel:[0,0,1] op_sel_hi:[0,1,0] neg_lo:[0,0,1] neg_hi:[0,0,1]
	v_pk_fma_f32 v[12:13], v[30:31], v[14:15], v[12:13] op_sel:[0,0,1] op_sel_hi:[0,1,0]
	v_mov_b32_e32 v12, v16
	ds_write2st64_b64 v1, v[14:15], v[12:13] offset0:4 offset1:5
	v_pk_mul_f32 v[14:15], v[30:31], v[12:13] op_sel:[1,0]
	s_nop 0
	v_pk_fma_f32 v[16:17], v[30:31], v[16:17], v[14:15] op_sel:[0,0,1] op_sel_hi:[1,1,0] neg_lo:[0,0,1] neg_hi:[0,0,1]
	v_pk_fma_f32 v[12:13], v[30:31], v[12:13], v[14:15] op_sel:[0,0,1] op_sel_hi:[0,1,0]
	v_mov_b32_e32 v17, v13
	v_pk_mul_f32 v[12:13], v[30:31], v[16:17] op_sel:[1,0]
	s_nop 0
	v_pk_fma_f32 v[14:15], v[30:31], v[16:17], v[12:13] op_sel:[0,0,1] op_sel_hi:[0,1,0] neg_lo:[0,0,1] neg_hi:[0,0,1]
	v_pk_fma_f32 v[12:13], v[30:31], v[16:17], v[12:13] op_sel:[0,0,1] op_sel_hi:[0,1,0]
	v_mov_b32_e32 v12, v14
	ds_write2st64_b64 v1, v[16:17], v[12:13] offset0:6 offset1:7
	v_pk_mul_f32 v[16:17], v[30:31], v[12:13] op_sel:[1,0]
	s_nop 0
	v_pk_fma_f32 v[14:15], v[30:31], v[14:15], v[16:17] op_sel:[0,0,1] op_sel_hi:[1,1,0] neg_lo:[0,0,1] neg_hi:[0,0,1]
	v_pk_fma_f32 v[12:13], v[30:31], v[12:13], v[16:17] op_sel:[0,0,1] op_sel_hi:[0,1,0]
	v_mov_b32_e32 v15, v13
	v_pk_mul_f32 v[12:13], v[30:31], v[14:15] op_sel:[1,0]
	s_nop 0
	v_pk_fma_f32 v[16:17], v[30:31], v[14:15], v[12:13] op_sel:[0,0,1] op_sel_hi:[0,1,0] neg_lo:[0,0,1] neg_hi:[0,0,1]
	v_pk_fma_f32 v[12:13], v[30:31], v[14:15], v[12:13] op_sel:[0,0,1] op_sel_hi:[0,1,0]
	v_mov_b32_e32 v12, v16
	ds_write2st64_b64 v1, v[14:15], v[12:13] offset0:8 offset1:9
	v_pk_mul_f32 v[14:15], v[30:31], v[12:13] op_sel:[1,0]
	s_nop 0
	v_pk_fma_f32 v[16:17], v[30:31], v[16:17], v[14:15] op_sel:[0,0,1] op_sel_hi:[1,1,0] neg_lo:[0,0,1] neg_hi:[0,0,1]
	v_pk_fma_f32 v[12:13], v[30:31], v[12:13], v[14:15] op_sel:[0,0,1] op_sel_hi:[0,1,0]
	v_mov_b32_e32 v17, v13
	v_pk_mul_f32 v[12:13], v[30:31], v[16:17] op_sel:[1,0]
	s_nop 0
	v_pk_fma_f32 v[14:15], v[30:31], v[16:17], v[12:13] op_sel:[0,0,1] op_sel_hi:[0,1,0] neg_lo:[0,0,1] neg_hi:[0,0,1]
	v_pk_fma_f32 v[12:13], v[30:31], v[16:17], v[12:13] op_sel:[0,0,1] op_sel_hi:[0,1,0]
	v_mov_b32_e32 v12, v14
	ds_write2st64_b64 v1, v[16:17], v[12:13] offset0:10 offset1:11
	v_pk_mul_f32 v[16:17], v[30:31], v[12:13] op_sel:[1,0]
	s_nop 0
	v_pk_fma_f32 v[14:15], v[30:31], v[14:15], v[16:17] op_sel:[0,0,1] op_sel_hi:[1,1,0] neg_lo:[0,0,1] neg_hi:[0,0,1]
	v_pk_fma_f32 v[12:13], v[30:31], v[12:13], v[16:17] op_sel:[0,0,1] op_sel_hi:[0,1,0]
	v_mov_b32_e32 v15, v13
	v_pk_mul_f32 v[12:13], v[30:31], v[14:15] op_sel:[1,0]
	s_nop 0
; #define layer launder_s(layer_)
; __device__ __forceinline__ void s5tab_item(const Params& p, int layer, int item, unsigned char* smem) {
;     ...
;     float pr = 1.f, pi = 0.f;
;     for (int j = 0; j <= 32; j++) {
;       AP[(dir * 33 + j) * 64 + pp] = make_float2(pr, pi);
;       float nr = pr * are - pi * aim, ni = pr * aim + pi * are; pr = nr; pi = ni;
;     }
;     int idx = ((layer * 2 + dir) * 32 + g) * 64 + pp;
;     for (int c = 0; c < 16; c++) {
;       float br = p.in[12][(size_t)idx * 16 + c], bi = p.in[13][(size_t)idx * 16 + c];
;       BB[(dir * 64 + pp) * 16 + c] = make_float2(fre * br - fim * bi, fre * bi + fim * br);
	v_pk_fma_f32 v[16:17], v[30:31], v[14:15], v[12:13] op_sel:[0,0,1] op_sel_hi:[0,1,0] neg_lo:[0,0,1] neg_hi:[0,0,1]
	v_pk_fma_f32 v[12:13], v[30:31], v[14:15], v[12:13] op_sel:[0,0,1] op_sel_hi:[0,1,0]
	v_mov_b32_e32 v12, v16
	ds_write2st64_b64 v1, v[14:15], v[12:13] offset0:12 offset1:13
	v_pk_mul_f32 v[14:15], v[30:31], v[12:13] op_sel:[1,0]
	s_nop 0
	v_pk_fma_f32 v[16:17], v[30:31], v[16:17], v[14:15] op_sel:[0,0,1] op_sel_hi:[1,1,0] neg_lo:[0,0,1] neg_hi:[0,0,1]
	v_pk_fma_f32 v[12:13], v[30:31], v[12:13], v[14:15] op_sel:[0,0,1] op_sel_hi:[0,1,0]
	v_mov_b32_e32 v17, v13
	v_pk_mul_f32 v[12:13], v[30:31], v[16:17] op_sel:[1,0]
	s_nop 0
	v_pk_fma_f32 v[14:15], v[30:31], v[16:17], v[12:13] op_sel:[0,0,1] op_sel_hi:[0,1,0] neg_lo:[0,0,1] neg_hi:[0,0,1]
	v_pk_fma_f32 v[12:13], v[30:31], v[16:17], v[12:13] op_sel:[0,0,1] op_sel_hi:[0,1,0]
	v_mov_b32_e32 v12, v14
	ds_write2st64_b64 v1, v[16:17], v[12:13] offset0:14 offset1:15
	v_pk_mul_f32 v[16:17], v[30:31], v[12:13] op_sel:[1,0]
	s_nop 0
	v_pk_fma_f32 v[14:15], v[30:31], v[14:15], v[16:17] op_sel:[0,0,1] op_sel_hi:[1,1,0] neg_lo:[0,0,1] neg_hi:[0,0,1]
	v_pk_fma_f32 v[12:13], v[30:31], v[12:13], v[16:17] op_sel:[0,0,1] op_sel_hi:[0,1,0]
	v_mov_b32_e32 v15, v13
	v_pk_mul_f32 v[12:13], v[30:31], v[14:15] op_sel:[1,0]
	s_nop 0
	v_pk_fma_f32 v[16:17], v[30:31], v[14:15], v[12:13] op_sel:[0,0,1] op_sel_hi:[0,1,0] neg_lo:[0,0,1] neg_hi:[0,0,1]
	v_pk_fma_f32 v[12:13], v[30:31], v[14:15], v[12:13] op_sel:[0,0,1] op_sel_hi:[0,1,0]
	v_mov_b32_e32 v12, v16
	ds_write2st64_b64 v1, v[14:15], v[12:13] offset0:16 offset1:17
	v_pk_mul_f32 v[14:15], v[30:31], v[12:13] op_sel:[1,0]
	s_nop 0
	v_pk_fma_f32 v[16:17], v[30:31], v[16:17], v[14:15] op_sel:[0,0,1] op_sel_hi:[1,1,0] neg_lo:[0,0,1] neg_hi:[0,0,1]
	v_pk_fma_f32 v[12:13], v[30:31], v[12:13], v[14:15] op_sel:[0,0,1] op_sel_hi:[0,1,0]
	v_mov_b32_e32 v17, v13
	v_pk_mul_f32 v[12:13], v[30:31], v[16:17] op_sel:[1,0]
	s_nop 0
	v_pk_fma_f32 v[14:15], v[30:31], v[16:17], v[12:13] op_sel:[0,0,1] op_sel_hi:[0,1,0] neg_lo:[0,0,1] neg_hi:[0,0,1]
	v_pk_fma_f32 v[12:13], v[30:31], v[16:17], v[12:13] op_sel:[0,0,1] op_sel_hi:[0,1,0]
	v_mov_b32_e32 v12, v14
	ds_write2st64_b64 v1, v[16:17], v[12:13] offset0:18 offset1:19
	v_pk_mul_f32 v[16:17], v[30:31], v[12:13] op_sel:[1,0]
	s_nop 0
	v_pk_fma_f32 v[14:15], v[30:31], v[14:15], v[16:17] op_sel:[0,0,1] op_sel_hi:[1,1,0] neg_lo:[0,0,1] neg_hi:[0,0,1]
	v_pk_fma_f32 v[12:13], v[30:31], v[12:13], v[16:17] op_sel:[0,0,1] op_sel_hi:[0,1,0]
	v_mov_b32_e32 v15, v13
	v_pk_mul_f32 v[12:13], v[30:31], v[14:15] op_sel:[1,0]
	s_nop 0
	v_pk_fma_f32 v[16:17], v[30:31], v[14:15], v[12:13] op_sel:[0,0,1] op_sel_hi:[0,1,0] neg_lo:[0,0,1] neg_hi:[0,0,1]
	v_pk_fma_f32 v[12:13], v[30:31], v[14:15], v[12:13] op_sel:[0,0,1] op_sel_hi:[0,1,0]
	v_mov_b32_e32 v12, v16
	ds_write2st64_b64 v1, v[14:15], v[12:13] offset0:20 offset1:21
	v_pk_mul_f32 v[14:15], v[30:31], v[12:13] op_sel:[1,0]
	s_nop 0
	v_pk_fma_f32 v[16:17], v[30:31], v[16:17], v[14:15] op_sel:[0,0,1] op_sel_hi:[1,1,0] neg_lo:[0,0,1] neg_hi:[0,0,1]
	v_pk_fma_f32 v[12:13], v[30:31], v[12:13], v[14:15] op_sel:[0,0,1] op_sel_hi:[0,1,0]
	v_mov_b32_e32 v17, v13
	v_pk_mul_f32 v[12:13], v[30:31], v[16:17] op_sel:[1,0]
	s_nop 0
	v_pk_fma_f32 v[14:15], v[30:31], v[16:17], v[12:13] op_sel:[0,0,1] op_sel_hi:[0,1,0] neg_lo:[0,0,1] neg_hi:[0,0,1]
	v_pk_fma_f32 v[12:13], v[30:31], v[16:17], v[12:13] op_sel:[0,0,1] op_sel_hi:[0,1,0]
	v_mov_b32_e32 v12, v14
	ds_write2st64_b64 v1, v[16:17], v[12:13] offset0:22 offset1:23
	v_pk_mul_f32 v[16:17], v[30:31], v[12:13] op_sel:[1,0]
	s_nop 0
	v_pk_fma_f32 v[14:15], v[30:31], v[14:15], v[16:17] op_sel:[0,0,1] op_sel_hi:[1,1,0] neg_lo:[0,0,1] neg_hi:[0,0,1]
	v_pk_fma_f32 v[12:13], v[30:31], v[12:13], v[16:17] op_sel:[0,0,1] op_sel_hi:[0,1,0]
	v_mov_b32_e32 v15, v13
	v_pk_mul_f32 v[12:13], v[30:31], v[14:15] op_sel:[1,0]
	s_nop 0
	v_pk_fma_f32 v[16:17], v[30:31], v[14:15], v[12:13] op_sel:[0,0,1] op_sel_hi:[0,1,0] neg_lo:[0,0,1] neg_hi:[0,0,1]
	v_pk_fma_f32 v[12:13], v[30:31], v[14:15], v[12:13] op_sel:[0,0,1] op_sel_hi:[0,1,0]
	v_mov_b32_e32 v12, v16
	ds_write2st64_b64 v1, v[14:15], v[12:13] offset0:24 offset1:25
	v_pk_mul_f32 v[14:15], v[30:31], v[12:13] op_sel:[1,0]
	s_nop 0
	v_pk_fma_f32 v[16:17], v[30:31], v[16:17], v[14:15] op_sel:[0,0,1] op_sel_hi:[1,1,0] neg_lo:[0,0,1] neg_hi:[0,0,1]
	v_pk_fma_f32 v[12:13], v[30:31], v[12:13], v[14:15] op_sel:[0,0,1] op_sel_hi:[0,1,0]
	v_mov_b32_e32 v17, v13
	v_pk_mul_f32 v[12:13], v[30:31], v[16:17] op_sel:[1,0]
	s_nop 0
	v_pk_fma_f32 v[14:15], v[30:31], v[16:17], v[12:13] op_sel:[0,0,1] op_sel_hi:[0,1,0] neg_lo:[0,0,1] neg_hi:[0,0,1]
	v_pk_fma_f32 v[12:13], v[30:31], v[16:17], v[12:13] op_sel:[0,0,1] op_sel_hi:[0,1,0]
	v_mov_b32_e32 v12, v14
	ds_write2st64_b64 v1, v[16:17], v[12:13] offset0:26 offset1:27
	v_pk_mul_f32 v[16:17], v[30:31], v[12:13] op_sel:[1,0]
	s_nop 0
	v_pk_fma_f32 v[14:15], v[30:31], v[14:15], v[16:17] op_sel:[0,0,1] op_sel_hi:[1,1,0] neg_lo:[0,0,1] neg_hi:[0,0,1]
	v_pk_fma_f32 v[12:13], v[30:31], v[12:13], v[16:17] op_sel:[0,0,1] op_sel_hi:[0,1,0]
	v_mov_b32_e32 v15, v13
	v_pk_mul_f32 v[12:13], v[30:31], v[14:15] op_sel:[1,0]
	s_nop 0
	v_pk_fma_f32 v[16:17], v[30:31], v[14:15], v[12:13] op_sel:[0,0,1] op_sel_hi:[0,1,0] neg_lo:[0,0,1] neg_hi:[0,0,1]
	v_pk_fma_f32 v[12:13], v[30:31], v[14:15], v[12:13] op_sel:[0,0,1] op_sel_hi:[0,1,0]
	v_mov_b32_e32 v12, v16
	ds_write2st64_b64 v1, v[14:15], v[12:13] offset0:28 offset1:29
	v_pk_mul_f32 v[14:15], v[30:31], v[12:13] op_sel:[1,0]
	s_nop 0
	v_pk_fma_f32 v[16:17], v[30:31], v[16:17], v[14:15] op_sel:[0,0,1] op_sel_hi:[1,1,0] neg_lo:[0,0,1] neg_hi:[0,0,1]
	v_pk_fma_f32 v[12:13], v[30:31], v[12:13], v[14:15] op_sel:[0,0,1] op_sel_hi:[0,1,0]
	v_mov_b32_e32 v17, v13
	v_pk_mul_f32 v[12:13], v[30:31], v[16:17] op_sel:[1,0]
	s_nop 0
	v_pk_fma_f32 v[14:15], v[30:31], v[16:17], v[12:13] op_sel:[0,0,1] op_sel_hi:[0,1,0] neg_lo:[0,0,1] neg_hi:[0,0,1]
	v_pk_fma_f32 v[12:13], v[30:31], v[16:17], v[12:13] op_sel:[0,0,1] op_sel_hi:[0,1,0]
	v_mov_b32_e32 v12, v14
	ds_write2st64_b64 v1, v[16:17], v[12:13] offset0:30 offset1:31
	v_pk_mul_f32 v[16:17], v[30:31], v[12:13] op_sel:[1,0]
	s_nop 0
	v_pk_fma_f32 v[14:15], v[30:31], v[14:15], v[16:17] op_sel:[0,0,1] op_sel_hi:[1,1,0] neg_lo:[0,0,1] neg_hi:[0,0,1]
	v_pk_fma_f32 v[12:13], v[30:31], v[12:13], v[16:17] op_sel:[0,0,1] op_sel_hi:[0,1,0]
	v_mov_b32_e32 v15, v13
	ds_write_b64 v1, v[14:15] offset:16384
	v_mov_b64_e32 v[12:13], s[34:35]
	global_load_dwordx4 v[14:17], v[12:13], off offset:96
	v_pk_mov_b32 v[30:31], v[30:31], v[34:35] op_sel:[1,0]
	v_lshl_add_u32 v1, v0, 7, 0
	v_pk_mul_f32 v[30:31], v[32:33], v[30:31] op_sel_hi:[0,1]
	v_pk_fma_f32 v[32:33], v[8:9], v[34:35], v[30:31]
	s_waitcnt vmcnt(0) lgkmcnt(0)
; __device__ __forceinline__ void s5_disc(const Params& p, int layer, int dir, int g, int pp, float& are, float& aim, float& fre, float& fim) {
;     ...
;   float den = lre * lre + lim * lim;
;   fre = ((are - 1.0f) * lre + aim * lim) / den;
;   fim = (aim * lre - (are - 1.0f) * lim) / den;
; __device__ __forceinline__ void s5tab_item(const Params& p, int layer, int item, unsigned char* smem) {
;     ...
;     for (int c = 0; c < 16; c++) {
;       float br = p.in[12][(size_t)idx * 16 + c], bi = p.in[13][(size_t)idx * 16 + c];
;       BB[(dir * 64 + pp) * 16 + c] = make_float2(fre * br - fim * bi, fre * bi + fim * br);
;     }
	v_lshl_add_u64 v[14:15], v[14:15], 0, v[10:11]
	v_lshl_add_u64 v[16:17], v[16:17], 0, v[10:11]
	global_load_dwordx4 v[100:103], v[16:17], off
	global_load_dwordx4 v[104:107], v[16:17], off offset:16
	global_load_dwordx4 v[108:111], v[16:17], off offset:32
	global_load_dwordx4 v[112:115], v[16:17], off offset:48
	global_load_dwordx4 v[116:119], v[14:15], off
	global_load_dwordx4 v[120:123], v[14:15], off offset:16
	global_load_dwordx4 v[124:127], v[14:15], off offset:32
	global_load_dwordx4 v[128:131], v[14:15], off offset:48
	v_pk_mul_f32 v[16:17], v[8:9], v[8:9]
	v_pk_fma_f32 v[8:9], v[8:9], v[34:35], v[30:31] op_sel_hi:[0,1,1] neg_lo:[0,0,1] neg_hi:[0,0,1]
	v_pk_add_f32 v[16:17], v[16:17], v[16:17] op_sel:[0,1] op_sel_hi:[0,1]
	v_div_scale_f32 v3, s[4:5], v17, v17, v9
	v_div_scale_f32 v8, s[4:5], v16, v16, v32
	v_rcp_f32_e32 v15, v3
	v_rcp_f32_e32 v29, v8
	v_div_scale_f32 v7, vcc, v9, v17, v9
	v_fma_f32 v31, -v3, v15, 1.0
	v_fma_f32 v33, -v8, v29, 1.0
	v_fmac_f32_e32 v15, v31, v15
	v_div_scale_f32 v30, s[4:5], v32, v16, v32
	v_fmac_f32_e32 v29, v33, v29
	v_mul_f32_e32 v31, v7, v15
	v_mul_f32_e32 v33, v30, v29
	v_fma_f32 v34, -v3, v31, v7
	v_fma_f32 v35, -v8, v33, v30
	v_fmac_f32_e32 v31, v34, v15
	v_fmac_f32_e32 v33, v35, v29
	v_fma_f32 v3, -v3, v31, v7
	v_fma_f32 v7, -v8, v33, v30
	v_div_fmas_f32 v3, v3, v15, v31
	s_mov_b64 vcc, s[4:5]
	v_div_fixup_f32 v9, v3, v17, v9
	v_div_fmas_f32 v3, v7, v29, v33
	v_div_fixup_f32 v8, v3, v16, v32
	s_waitcnt vmcnt(0) lgkmcnt(0)
	v_mov_b32_e32 v4, v100
	v_mov_b32_e32 v14, v116
	v_pk_mul_f32 v[16:17], v[8:9], v[4:5] op_sel:[1,0] op_sel_hi:[0,0]
	v_pk_fma_f32 v[30:31], v[8:9], v[14:15], v[16:17] neg_lo:[0,0,1] neg_hi:[0,0,1]
	v_pk_fma_f32 v[14:15], v[8:9], v[14:15], v[16:17] op_sel_hi:[1,0,1]
	s_nop 0
	v_mov_b32_e32 v31, v15
	ds_write_b64 v1, v[30:31] offset:33792
	s_waitcnt lgkmcnt(0)
	v_mov_b32_e32 v4, v101
	v_mov_b32_e32 v14, v117
	v_pk_mul_f32 v[16:17], v[8:9], v[4:5] op_sel:[1,0] op_sel_hi:[0,0]
	v_pk_fma_f32 v[30:31], v[8:9], v[14:15], v[16:17] neg_lo:[0,0,1] neg_hi:[0,0,1]
	v_pk_fma_f32 v[14:15], v[8:9], v[14:15], v[16:17] op_sel_hi:[1,0,1]
	s_nop 0
	v_mov_b32_e32 v31, v15
	ds_write_b64 v1, v[30:31] offset:33800
	s_waitcnt lgkmcnt(0)
	v_mov_b32_e32 v4, v102
	v_mov_b32_e32 v14, v118
	v_pk_mul_f32 v[16:17], v[8:9], v[4:5] op_sel:[1,0] op_sel_hi:[0,0]
	v_pk_fma_f32 v[30:31], v[8:9], v[14:15], v[16:17] neg_lo:[0,0,1] neg_hi:[0,0,1]
	v_pk_fma_f32 v[14:15], v[8:9], v[14:15], v[16:17] op_sel_hi:[1,0,1]
	s_nop 0
	v_mov_b32_e32 v31, v15
	ds_write_b64 v1, v[30:31] offset:33808
	s_waitcnt lgkmcnt(0)
	v_mov_b32_e32 v4, v103
	v_mov_b32_e32 v14, v119
	v_pk_mul_f32 v[16:17], v[8:9], v[4:5] op_sel:[1,0] op_sel_hi:[0,0]
	v_pk_fma_f32 v[30:31], v[8:9], v[14:15], v[16:17] neg_lo:[0,0,1] neg_hi:[0,0,1]
	v_pk_fma_f32 v[14:15], v[8:9], v[14:15], v[16:17] op_sel_hi:[1,0,1]
	s_nop 0
	v_mov_b32_e32 v31, v15
	ds_write_b64 v1, v[30:31] offset:33816
	s_waitcnt lgkmcnt(0)
	v_mov_b32_e32 v4, v104
	v_mov_b32_e32 v14, v120
	v_pk_mul_f32 v[16:17], v[8:9], v[4:5] op_sel:[1,0] op_sel_hi:[0,0]
	v_pk_fma_f32 v[30:31], v[8:9], v[14:15], v[16:17] neg_lo:[0,0,1] neg_hi:[0,0,1]
	v_pk_fma_f32 v[14:15], v[8:9], v[14:15], v[16:17] op_sel_hi:[1,0,1]
	s_nop 0
	v_mov_b32_e32 v31, v15
	ds_write_b64 v1, v[30:31] offset:33824
	s_waitcnt lgkmcnt(0)
	v_mov_b32_e32 v4, v105
	v_mov_b32_e32 v14, v121
	v_pk_mul_f32 v[16:17], v[8:9], v[4:5] op_sel:[1,0] op_sel_hi:[0,0]
	v_pk_fma_f32 v[30:31], v[8:9], v[14:15], v[16:17] neg_lo:[0,0,1] neg_hi:[0,0,1]
	v_pk_fma_f32 v[14:15], v[8:9], v[14:15], v[16:17] op_sel_hi:[1,0,1]
	s_nop 0
	v_mov_b32_e32 v31, v15
	ds_write_b64 v1, v[30:31] offset:33832
	s_waitcnt lgkmcnt(0)
; __device__ __forceinline__ void s5tab_item(const Params& p, int layer, int item, unsigned char* smem) {
;     ...
;     for (int c = 0; c < 16; c++) {
;       float br = p.in[12][(size_t)idx * 16 + c], bi = p.in[13][(size_t)idx * 16 + c];
;       BB[(dir * 64 + pp) * 16 + c] = make_float2(fre * br - fim * bi, fre * bi + fim * br);
;     }
	v_mov_b32_e32 v4, v106
	v_mov_b32_e32 v14, v122
	v_pk_mul_f32 v[16:17], v[8:9], v[4:5] op_sel:[1,0] op_sel_hi:[0,0]
	v_pk_fma_f32 v[30:31], v[8:9], v[14:15], v[16:17] neg_lo:[0,0,1] neg_hi:[0,0,1]
	v_pk_fma_f32 v[14:15], v[8:9], v[14:15], v[16:17] op_sel_hi:[1,0,1]
	s_nop 0
	v_mov_b32_e32 v31, v15
	ds_write_b64 v1, v[30:31] offset:33840
	s_waitcnt lgkmcnt(0)
	v_mov_b32_e32 v4, v107
	v_mov_b32_e32 v14, v123
	v_pk_mul_f32 v[16:17], v[8:9], v[4:5] op_sel:[1,0] op_sel_hi:[0,0]
	v_pk_fma_f32 v[30:31], v[8:9], v[14:15], v[16:17] neg_lo:[0,0,1] neg_hi:[0,0,1]
	v_pk_fma_f32 v[14:15], v[8:9], v[14:15], v[16:17] op_sel_hi:[1,0,1]
	s_nop 0
	v_mov_b32_e32 v31, v15
	ds_write_b64 v1, v[30:31] offset:33848
	s_waitcnt lgkmcnt(0)
	v_mov_b32_e32 v4, v108
	v_mov_b32_e32 v14, v124
	v_pk_mul_f32 v[16:17], v[8:9], v[4:5] op_sel:[1,0] op_sel_hi:[0,0]
	v_pk_fma_f32 v[30:31], v[8:9], v[14:15], v[16:17] neg_lo:[0,0,1] neg_hi:[0,0,1]
	v_pk_fma_f32 v[14:15], v[8:9], v[14:15], v[16:17] op_sel_hi:[1,0,1]
	s_nop 0
	v_mov_b32_e32 v31, v15
	ds_write_b64 v1, v[30:31] offset:33856
	s_waitcnt lgkmcnt(0)
	v_mov_b32_e32 v4, v109
	v_mov_b32_e32 v14, v125
	v_pk_mul_f32 v[16:17], v[8:9], v[4:5] op_sel:[1,0] op_sel_hi:[0,0]
	v_pk_fma_f32 v[30:31], v[8:9], v[14:15], v[16:17] neg_lo:[0,0,1] neg_hi:[0,0,1]
	v_pk_fma_f32 v[14:15], v[8:9], v[14:15], v[16:17] op_sel_hi:[1,0,1]
	s_nop 0
	v_mov_b32_e32 v31, v15
	ds_write_b64 v1, v[30:31] offset:33864
	s_waitcnt lgkmcnt(0)
	v_mov_b32_e32 v4, v110
	v_mov_b32_e32 v14, v126
	v_pk_mul_f32 v[16:17], v[8:9], v[4:5] op_sel:[1,0] op_sel_hi:[0,0]
	v_pk_fma_f32 v[30:31], v[8:9], v[14:15], v[16:17] neg_lo:[0,0,1] neg_hi:[0,0,1]
	v_pk_fma_f32 v[14:15], v[8:9], v[14:15], v[16:17] op_sel_hi:[1,0,1]
	s_nop 0
	v_mov_b32_e32 v31, v15
	ds_write_b64 v1, v[30:31] offset:33872
	s_waitcnt lgkmcnt(0)
	v_mov_b32_e32 v4, v111
	v_mov_b32_e32 v14, v127
	v_pk_mul_f32 v[16:17], v[8:9], v[4:5] op_sel:[1,0] op_sel_hi:[0,0]
	v_pk_fma_f32 v[30:31], v[8:9], v[14:15], v[16:17] neg_lo:[0,0,1] neg_hi:[0,0,1]
	v_pk_fma_f32 v[14:15], v[8:9], v[14:15], v[16:17] op_sel_hi:[1,0,1]
	s_nop 0
	v_mov_b32_e32 v31, v15
	ds_write_b64 v1, v[30:31] offset:33880
	s_waitcnt lgkmcnt(0)
	v_mov_b32_e32 v4, v112
	v_mov_b32_e32 v14, v128
	v_pk_mul_f32 v[16:17], v[8:9], v[4:5] op_sel:[1,0] op_sel_hi:[0,0]
	v_pk_fma_f32 v[30:31], v[8:9], v[14:15], v[16:17] neg_lo:[0,0,1] neg_hi:[0,0,1]
	v_pk_fma_f32 v[14:15], v[8:9], v[14:15], v[16:17] op_sel_hi:[1,0,1]
	s_nop 0
	v_mov_b32_e32 v31, v15
	ds_write_b64 v1, v[30:31] offset:33888
	s_waitcnt lgkmcnt(0)
	v_mov_b32_e32 v4, v113
	v_mov_b32_e32 v14, v129
	v_pk_mul_f32 v[16:17], v[8:9], v[4:5] op_sel:[1,0] op_sel_hi:[0,0]
	v_pk_fma_f32 v[30:31], v[8:9], v[14:15], v[16:17] neg_lo:[0,0,1] neg_hi:[0,0,1]
	v_pk_fma_f32 v[14:15], v[8:9], v[14:15], v[16:17] op_sel_hi:[1,0,1]
	s_nop 0
	v_mov_b32_e32 v31, v15
	ds_write_b64 v1, v[30:31] offset:33896
	s_waitcnt lgkmcnt(0)
	v_mov_b32_e32 v4, v114
	v_mov_b32_e32 v14, v130
	v_pk_mul_f32 v[16:17], v[8:9], v[4:5] op_sel:[1,0] op_sel_hi:[0,0]
	v_pk_fma_f32 v[30:31], v[8:9], v[14:15], v[16:17] neg_lo:[0,0,1] neg_hi:[0,0,1]
	v_pk_fma_f32 v[14:15], v[8:9], v[14:15], v[16:17] op_sel_hi:[1,0,1]
	s_nop 0
	v_mov_b32_e32 v31, v15
	ds_write_b64 v1, v[30:31] offset:33904
	s_waitcnt lgkmcnt(0)
	v_mov_b32_e32 v4, v115
	v_mov_b32_e32 v10, v131
	v_pk_mul_f32 v[12:13], v[8:9], v[4:5] op_sel:[1,0] op_sel_hi:[0,0]
	v_pk_fma_f32 v[14:15], v[8:9], v[10:11], v[12:13] neg_lo:[0,0,1] neg_hi:[0,0,1]
	v_pk_fma_f32 v[8:9], v[8:9], v[10:11], v[12:13] op_sel_hi:[1,0,1]
	s_nop 0
	v_mov_b32_e32 v15, v9
	ds_write_b64 v1, v[14:15] offset:33912

; #define layer launder_s(layer_)
; __device__ __forceinline__ void s5tab_item(const Params& p, int layer, int item, unsigned char* smem) {
;     ...
;   for (int e = tid; e < 2 * 16 * 64; e += NT) {
;     int dir = e >> 10, c = (e >> 6) & 15, pp = e & 63;
;     size_t ci = ((size_t)((layer * 2 + dir) * 32 + g) * 16 + c) * 64 + pp;
;     CC[e] = make_float2(p.in[14][ci], p.in[15][ci]);
;   }
.LBB0_90:
	v_mov_b64_e32 v[8:9], s[34:35]
	global_load_dwordx4 v[8:11], v[8:9], off offset:112
	v_mov_b32_e32 v124, v3
	v_ashrrev_i32_e32 v4, 5, v124
	v_and_b32_e32 v4, 0xffffffe0, v4
	v_add_u32_e32 v12, s8, v4
	v_ashrrev_i32_e32 v13, 31, v12
	v_lshlrev_b64 v[12:13], 10, v[12:13]
	v_and_or_b32 v4, v124, s65, v12
	v_or_b32_e32 v12, v4, v2
	v_lshlrev_b64 v[100:101], 2, v[12:13]
	v_add_u32_e32 v124, 0x200, v3
	v_ashrrev_i32_e32 v4, 5, v124
	v_and_b32_e32 v4, 0xffffffe0, v4
	v_add_u32_e32 v12, s8, v4
	v_ashrrev_i32_e32 v13, 31, v12
	v_lshlrev_b64 v[12:13], 10, v[12:13]
	v_and_or_b32 v4, v124, s65, v12
	v_or_b32_e32 v12, v4, v2
	v_lshlrev_b64 v[102:103], 2, v[12:13]
	v_add_u32_e32 v124, 0x400, v3
	v_ashrrev_i32_e32 v4, 5, v124
	v_and_b32_e32 v4, 0xffffffe0, v4
	v_add_u32_e32 v12, s8, v4
	v_ashrrev_i32_e32 v13, 31, v12
	v_lshlrev_b64 v[12:13], 10, v[12:13]
	v_and_or_b32 v4, v124, s65, v12
	v_or_b32_e32 v12, v4, v2
	v_lshlrev_b64 v[104:105], 2, v[12:13]
	v_add_u32_e32 v124, 0x600, v3
	v_ashrrev_i32_e32 v4, 5, v124
	v_and_b32_e32 v4, 0xffffffe0, v4
	v_add_u32_e32 v12, s8, v4
	v_ashrrev_i32_e32 v13, 31, v12
	v_lshlrev_b64 v[12:13], 10, v[12:13]
	v_and_or_b32 v4, v124, s65, v12
	v_or_b32_e32 v12, v4, v2
	v_lshlrev_b64 v[106:107], 2, v[12:13]
	s_waitcnt vmcnt(0) lgkmcnt(0)
	v_lshl_add_u64 v[120:121], v[8:9], 0, v[100:101]
	v_lshl_add_u64 v[122:123], v[10:11], 0, v[100:101]
	global_load_dword v110, v[120:121], off
	global_load_dword v111, v[122:123], off
	v_lshl_add_u64 v[120:121], v[8:9], 0, v[102:103]
	v_lshl_add_u64 v[122:123], v[10:11], 0, v[102:103]
	global_load_dword v112, v[120:121], off
	global_load_dword v113, v[122:123], off
	v_lshl_add_u64 v[120:121], v[8:9], 0, v[104:105]
	v_lshl_add_u64 v[122:123], v[10:11], 0, v[104:105]
	global_load_dword v114, v[120:121], off
	global_load_dword v115, v[122:123], off
	v_lshl_add_u64 v[120:121], v[8:9], 0, v[106:107]
	v_lshl_add_u64 v[122:123], v[10:11], 0, v[106:107]
	global_load_dword v116, v[120:121], off
	global_load_dword v117, v[122:123], off
	s_waitcnt vmcnt(6)
	ds_write_b64 v1, v[110:111]
	s_waitcnt vmcnt(4)
	ds_write_b64 v1, v[112:113] offset:4096
	s_waitcnt vmcnt(2)
	ds_write_b64 v1, v[114:115] offset:8192
	s_waitcnt vmcnt(0)
	ds_write_b64 v1, v[116:117] offset:12288

; __device__ __forceinline__ void s5tab_item(const Params& p, int layer, int item, unsigned char* smem) {
;     ...
;   for (int e = tid; e < 16384; e += NT) {
;     int dir = e >> 13, j = (e >> 8) & 31, c = (e >> 4) & 15, c2 = e & 15;
;     float sum = 0.f;
; #pragma unroll 8
;     for (int pp = 0; pp < 64; pp++) {
;       float2 cc = CC[(dir * 16 + c) * 64 + pp], aa = AP[(dir * 33 + j) * 64 + pp], bb = BB[(dir * 64 + pp) * 16 + c2];
;       float wr_ = cc.x * aa.x - cc.y * aa.y, wi_ = cc.x * aa.y + cc.y * aa.x;
;       sum += wr_ * bb.x - wi_ * bb.y;
;     }
;     KT[e] = sum;
.LBB0_94:
	v_add_u32_e32 v16, s8, v9
	v_add_u32_e32 v11, s8, v7
	ds_read2_b64 v[12:15], v8 offset1:16
	ds_read2_b64 v[30:33], v8 offset0:32 offset1:48
	ds_read2_b64 v[34:37], v8 offset0:64 offset1:80
	ds_read2_b64 v[38:41], v8 offset0:96 offset1:112
	ds_read_b128 v[42:45], v16
	ds_read_b128 v[46:49], v16 offset:16
	ds_read_b128 v[50:53], v16 offset:32
	ds_read_b128 v[54:57], v16 offset:48
	ds_read_b128 v[58:61], v11
	ds_read_b128 v[62:65], v11 offset:16
	ds_read_b128 v[66:69], v11 offset:32
	ds_read_b128 v[70:73], v11 offset:48
	v_add_u32_e32 v8, 0x400, v8
	s_waitcnt lgkmcnt(3)
	v_pk_mul_f32 v[16:17], v[58:59], v[42:43] op_sel:[1,1] op_sel_hi:[0,1]
	v_pk_fma_f32 v[74:75], v[58:59], v[42:43], v[16:17] op_sel_hi:[1,0,1] neg_lo:[0,0,1]
	v_pk_mul_f32 v[76:77], v[12:13], v[74:75]
	v_sub_f32_e32 v11, v76, v77
	v_add_f32_e32 v10, v10, v11
	v_pk_mul_f32 v[16:17], v[60:61], v[44:45] op_sel:[1,1] op_sel_hi:[0,1]
	v_pk_fma_f32 v[74:75], v[60:61], v[44:45], v[16:17] op_sel_hi:[1,0,1] neg_lo:[0,0,1]
	v_pk_mul_f32 v[76:77], v[14:15], v[74:75]
	v_sub_f32_e32 v11, v76, v77
	v_add_f32_e32 v10, v10, v11
	s_waitcnt lgkmcnt(2)
	v_pk_mul_f32 v[16:17], v[62:63], v[46:47] op_sel:[1,1] op_sel_hi:[0,1]
	v_pk_fma_f32 v[74:75], v[62:63], v[46:47], v[16:17] op_sel_hi:[1,0,1] neg_lo:[0,0,1]
	v_pk_mul_f32 v[76:77], v[30:31], v[74:75]
	v_sub_f32_e32 v11, v76, v77
	v_add_f32_e32 v10, v10, v11
	v_pk_mul_f32 v[16:17], v[64:65], v[48:49] op_sel:[1,1] op_sel_hi:[0,1]
	v_pk_fma_f32 v[74:75], v[64:65], v[48:49], v[16:17] op_sel_hi:[1,0,1] neg_lo:[0,0,1]
	v_pk_mul_f32 v[76:77], v[32:33], v[74:75]
	v_sub_f32_e32 v11, v76, v77
	v_add_f32_e32 v10, v10, v11
	s_waitcnt lgkmcnt(1)
	v_pk_mul_f32 v[16:17], v[66:67], v[50:51] op_sel:[1,1] op_sel_hi:[0,1]
	v_pk_fma_f32 v[74:75], v[66:67], v[50:51], v[16:17] op_sel_hi:[1,0,1] neg_lo:[0,0,1]
	v_pk_mul_f32 v[76:77], v[34:35], v[74:75]
	v_sub_f32_e32 v11, v76, v77
	v_add_f32_e32 v10, v10, v11
	v_pk_mul_f32 v[16:17], v[68:69], v[52:53] op_sel:[1,1] op_sel_hi:[0,1]
	v_pk_fma_f32 v[74:75], v[68:69], v[52:53], v[16:17] op_sel_hi:[1,0,1] neg_lo:[0,0,1]
	v_pk_mul_f32 v[76:77], v[36:37], v[74:75]
	v_sub_f32_e32 v11, v76, v77
	v_add_f32_e32 v10, v10, v11
	s_waitcnt lgkmcnt(0)
	v_pk_mul_f32 v[16:17], v[70:71], v[54:55] op_sel:[1,1] op_sel_hi:[0,1]
	v_pk_fma_f32 v[74:75], v[70:71], v[54:55], v[16:17] op_sel_hi:[1,0,1] neg_lo:[0,0,1]
	v_pk_mul_f32 v[76:77], v[38:39], v[74:75]
	v_sub_f32_e32 v11, v76, v77
	v_add_f32_e32 v10, v10, v11
	v_pk_mul_f32 v[16:17], v[72:73], v[56:57] op_sel:[1,1] op_sel_hi:[0,1]
	v_pk_fma_f32 v[74:75], v[72:73], v[56:57], v[16:17] op_sel_hi:[1,0,1] neg_lo:[0,0,1]
	v_pk_mul_f32 v[76:77], v[40:41], v[74:75]
	v_sub_f32_e32 v11, v76, v77
	v_add_f32_e32 v10, v10, v11
	s_add_i32 s8, s8, 64
	s_cmpk_eq_i32 s8, 0x200
	s_cbranch_scc0 .LBB0_94
	v_lshl_add_u32 v7, v4, 2, 0
	v_add_u32_e32 v7, 0x10400, v7
	ds_write_b32 v7, v10

; __device__ __forceinline__ float bf2f(u16 h) { return __uint_as_float(((unsigned)h) << 16); }
; __device__ __forceinline__ unsigned pack2(float a, float b) { unsigned r; asm("v_cvt_pk_bf16_f32 %0, %1, %2" : "=v"(r) : "v"(a), "v"(b)); return r; }
; __device__ __forceinline__ u32x4 conv3x8(const u16* seq, int t8, int Ls, float w0, float w1, float w2, float cb) {
;   u32x4 v = *(const u32x4*)(seq + t8);
;   float z[10];
;   z[0] = t8 > 0 ? bf2f(seq[t8 - 1]) : 0.f;
;   z[1] = __uint_as_float(v.x << 16); z[2] = __uint_as_float(v.x & 0xffff0000u);
;   z[3] = __uint_as_float(v.y << 16); z[4] = __uint_as_float(v.y & 0xffff0000u);
;   z[5] = __uint_as_float(v.z << 16); z[6] = __uint_as_float(v.z & 0xffff0000u);
;   z[7] = __uint_as_float(v.w << 16); z[8] = __uint_as_float(v.w & 0xffff0000u);
;   z[9] = (t8 + 8 < Ls) ? bf2f(seq[t8 + 8]) : 0.f;
;   float o[8];
; #pragma unroll
;   for (int i = 0; i < 8; i++) o[i] = cb + w0 * z[i] + w1 * z[i + 1] + w2 * z[i + 2];
;   u32x4 r; r.x = pack2(o[0], o[1]); r.y = pack2(o[2], o[3]); r.z = pack2(o[4], o[5]); r.w = pack2(o[6], o[7]);
;   return r;
; }
; __device__ __forceinline__ void hyena_task(const Params& p, int layer, int c, bool isctx, unsigned char* smem) {
;     ...
;     {
;       int per = Ls >> 3;
;       int gch = 512 * (o + 1) + c;
;       float w0 = cw[0 * 1536 + c], w1 = cw[1 * 1536 + c], w2 = cw[2 * 1536 + c], cb = cbv[c];
;       float gw0 = cw[0 * 1536 + gch], gw1 = cw[1 * 1536 + gch], gw2 = cw[2 * 1536 + gch], gcb = cbv[gch];
; #pragma unroll 2
;       for (int e = tid; e < 8 * per; e += NT) {
;         int b = e / per, t8 = (e - b * per) * 8;
;         size_t rowoff = (size_t)rowbase + (size_t)b * Ls;
;         if (o == 0) *(u32x4*)(YA + b * HY_YS + t8) = conv3x8(ZHT + (size_t)c * TA + rowoff, t8, Ls, w0, w1, w2, cb);
;         *(u32x4*)(GT + b * HY_YS + t8) = conv3x8(ZHT + (size_t)gch * TA + rowoff, t8, Ls, gw0, gw1, gw2, gcb);
;       }
;     }
.LBB0_369:
	s_or_b64 exec, exec, s[6:7]
	v_readlane_b32 s4, v255, 14
	v_readlane_b32 s5, v255, 15
	s_lshl_b32 s4, s18, 9
	v_writelane_b32 v255, s4, 14
	s_waitcnt lgkmcnt(0)
	s_barrier
	v_writelane_b32 v255, s5, 15
	s_and_saveexec_b64 s[6:7], s[12:13]
	s_cbranch_execz .LBB0_384
	v_readlane_b32 s4, v255, 14
	v_readlane_b32 s5, v255, 15
	s_add_i32 s18, s10, s4
	s_lshl_b64 s[4:5], s[4:5], 2
	v_lshl_add_u64 v[0:1], v[76:77], 0, s[4:5]
	v_lshl_add_u64 v[2:3], v[78:79], 0, s[4:5]
	global_load_dword v24, v[76:77], off
	global_load_dword v25, v[78:79], off
	global_load_dword v27, v[2:3], off offset:2048
	v_add_co_u32_e32 v2, vcc, 0x3000, v0
	global_load_dword v26, v[0:1], off offset:2048
	s_nop 0
	v_addc_co_u32_e32 v3, vcc, 0, v1, vcc
	v_add_co_u32_e32 v0, vcc, 0x2000, v0
	global_load_dword v4, v[2:3], off offset:2048
	s_nop 0
	v_addc_co_u32_e32 v1, vcc, 0, v1, vcc
	global_load_dword v5, v[0:1], off
	global_load_dword v6, v[84:85], off
	global_load_dword v7, v[82:83], off
	v_mad_i64_i32 v[8:9], s[4:5], s18, v248, v[72:73]
	v_lshrrev_b32_e32 v10, 8, v66
	v_lshlrev_b32_e32 v10, 12, v10
	v_and_b32_e32 v12, 0xff, v66
	v_lshl_or_b32 v10, v12, 4, v10
	v_mov_b32_e32 v11, 0
	v_lshl_add_u64 v[30:31], v[8:9], 0, v[10:11]
	s_mov_b64 s[4:5], 0x2000
	v_cmp_ne_u32_e64 s[22:23], 0, v12
	v_mov_b32_e32 v13, 0xff
	v_cmp_gt_u32_e64 s[60:61], v13, v12
	v_lshlrev_b32_e32 v23, 4, v66
	v_lshrrev_b32_e32 v22, 8, v66
	v_lshl_add_u32 v23, v22, 4, v23
	v_add_u32_e32 v22, s93, v23
	s_cmp_eq_u64 s[40:41], 0
	s_cbranch_scc0 .Lhc_gload
	v_lshl_add_u64 v[28:29], v[80:81], 0, v[10:11]
	global_load_dwordx4 v[32:35], v[28:29], off
	global_load_ushort v48, v[28:29], off offset:-2
	global_load_ushort v52, v[28:29], off offset:16
	v_lshl_add_u64 v[28:29], v[28:29], 0, s[4:5]
	global_load_dwordx4 v[36:39], v[28:29], off
	global_load_ushort v49, v[28:29], off offset:-2
	global_load_ushort v53, v[28:29], off offset:16
	v_lshl_add_u64 v[28:29], v[28:29], 0, s[4:5]
	global_load_dwordx4 v[40:43], v[28:29], off
	global_load_ushort v50, v[28:29], off offset:-2
	global_load_ushort v54, v[28:29], off offset:16
	v_lshl_add_u64 v[28:29], v[28:29], 0, s[4:5]
	global_load_dwordx4 v[44:47], v[28:29], off
	global_load_ushort v51, v[28:29], off offset:-2
	global_load_ushort v55, v[28:29], off offset:16
.Lhc_gload:
	global_load_dwordx4 v[56:59], v[30:31], off
	global_load_ushort v96, v[30:31], off offset:-2
	global_load_ushort v100, v[30:31], off offset:16
	v_lshl_add_u64 v[30:31], v[30:31], 0, s[4:5]
	global_load_dwordx4 v[60:63], v[30:31], off
	global_load_ushort v97, v[30:31], off offset:-2
	global_load_ushort v101, v[30:31], off offset:16
	v_lshl_add_u64 v[30:31], v[30:31], 0, s[4:5]
	global_load_dwordx4 v[88:91], v[30:31], off
	global_load_ushort v98, v[30:31], off offset:-2
	global_load_ushort v102, v[30:31], off offset:16
	v_lshl_add_u64 v[30:31], v[30:31], 0, s[4:5]
	global_load_dwordx4 v[92:95], v[30:31], off
	global_load_ushort v99, v[30:31], off offset:-2
	global_load_ushort v103, v[30:31], off offset:16
	s_cbranch_scc0 .Lhc_gcomp
	s_waitcnt vmcnt(21)
	v_lshlrev_b32_e32 v10, 16, v48
	v_lshlrev_b32_e32 v19, 16, v52
	v_lshlrev_b32_e32 v11, 16, v32
	v_and_b32_e32 v12, 0xffff0000, v32
	v_lshlrev_b32_e32 v13, 16, v33
	v_and_b32_e32 v14, 0xffff0000, v33
	v_lshlrev_b32_e32 v15, 16, v34
	v_and_b32_e32 v16, 0xffff0000, v34
	v_lshlrev_b32_e32 v17, 16, v35
	v_and_b32_e32 v18, 0xffff0000, v35
	v_cndmask_b32_e64 v10, 0, v10, s[22:23]
	v_cndmask_b32_e64 v19, 0, v19, s[60:61]
	v_fma_f32 v20, v24, v10, v25
	v_mul_f32_e32 v21, v7, v11
	v_mul_f32_e32 v0, v6, v12
	v_add_f32_e32 v21, v21, v20
	v_add_f32_e32 v0, v0, v21
	v_fma_f32 v20, v24, v11, v25
	v_mul_f32_e32 v21, v7, v12
	v_mul_f32_e32 v1, v6, v13
	v_add_f32_e32 v21, v21, v20
	v_add_f32_e32 v1, v1, v21
	v_fma_f32 v20, v24, v12, v25
	v_mul_f32_e32 v21, v7, v13
	v_mul_f32_e32 v2, v6, v14
	v_add_f32_e32 v21, v21, v20
	v_add_f32_e32 v2, v2, v21
	v_fma_f32 v20, v24, v13, v25
	v_mul_f32_e32 v21, v7, v14
	v_mul_f32_e32 v3, v6, v15
	v_add_f32_e32 v21, v21, v20
	v_add_f32_e32 v3, v3, v21
	v_fma_f32 v20, v24, v14, v25
	v_mul_f32_e32 v21, v7, v15
	v_mul_f32_e32 v28, v6, v16
	v_add_f32_e32 v21, v21, v20
	v_add_f32_e32 v28, v28, v21
	v_fma_f32 v20, v24, v15, v25
	v_mul_f32_e32 v21, v7, v16
	v_mul_f32_e32 v29, v6, v17
	v_add_f32_e32 v21, v21, v20
	v_add_f32_e32 v29, v29, v21
	v_fma_f32 v20, v24, v16, v25
	v_mul_f32_e32 v21, v7, v17
	v_mul_f32_e32 v30, v6, v18
	v_add_f32_e32 v21, v21, v20
	v_add_f32_e32 v30, v30, v21
	v_fma_f32 v20, v24, v17, v25
	v_mul_f32_e32 v21, v7, v18
	v_mul_f32_e32 v31, v6, v19
	v_add_f32_e32 v21, v21, v20
	v_add_f32_e32 v31, v31, v21
	v_cvt_pk_bf16_f32 v0, v0, v1
	v_cvt_pk_bf16_f32 v1, v2, v3
	v_cvt_pk_bf16_f32 v2, v28, v29
	v_cvt_pk_bf16_f32 v3, v30, v31
	ds_write_b128 v23, v[0:3] offset:33024
	s_waitcnt vmcnt(18)
; __device__ __forceinline__ float bf2f(u16 h) { return __uint_as_float(((unsigned)h) << 16); }
; __device__ __forceinline__ unsigned pack2(float a, float b) { unsigned r; asm("v_cvt_pk_bf16_f32 %0, %1, %2" : "=v"(r) : "v"(a), "v"(b)); return r; }
; __device__ __forceinline__ u32x4 conv3x8(const u16* seq, int t8, int Ls, float w0, float w1, float w2, float cb) {
;   u32x4 v = *(const u32x4*)(seq + t8);
;   float z[10];
;   z[0] = t8 > 0 ? bf2f(seq[t8 - 1]) : 0.f;
;   z[1] = __uint_as_float(v.x << 16); z[2] = __uint_as_float(v.x & 0xffff0000u);
;   z[3] = __uint_as_float(v.y << 16); z[4] = __uint_as_float(v.y & 0xffff0000u);
;   z[5] = __uint_as_float(v.z << 16); z[6] = __uint_as_float(v.z & 0xffff0000u);
;   z[7] = __uint_as_float(v.w << 16); z[8] = __uint_as_float(v.w & 0xffff0000u);
;   z[9] = (t8 + 8 < Ls) ? bf2f(seq[t8 + 8]) : 0.f;
;   float o[8];
; #pragma unroll
;   for (int i = 0; i < 8; i++) o[i] = cb + w0 * z[i] + w1 * z[i + 1] + w2 * z[i + 2];
;   u32x4 r; r.x = pack2(o[0], o[1]); r.y = pack2(o[2], o[3]); r.z = pack2(o[4], o[5]); r.w = pack2(o[6], o[7]);
;   return r;
; }
	v_lshlrev_b32_e32 v10, 16, v49
	v_lshlrev_b32_e32 v19, 16, v53
	v_lshlrev_b32_e32 v11, 16, v36
	v_and_b32_e32 v12, 0xffff0000, v36
	v_lshlrev_b32_e32 v13, 16, v37
	v_and_b32_e32 v14, 0xffff0000, v37
	v_lshlrev_b32_e32 v15, 16, v38
	v_and_b32_e32 v16, 0xffff0000, v38
	v_lshlrev_b32_e32 v17, 16, v39
	v_and_b32_e32 v18, 0xffff0000, v39
	v_cndmask_b32_e64 v10, 0, v10, s[22:23]
	v_cndmask_b32_e64 v19, 0, v19, s[60:61]
	v_fma_f32 v20, v24, v10, v25
	v_mul_f32_e32 v21, v7, v11
	v_mul_f32_e32 v0, v6, v12
	v_add_f32_e32 v21, v21, v20
	v_add_f32_e32 v0, v0, v21
	v_fma_f32 v20, v24, v11, v25
	v_mul_f32_e32 v21, v7, v12
	v_mul_f32_e32 v1, v6, v13
	v_add_f32_e32 v21, v21, v20
	v_add_f32_e32 v1, v1, v21
	v_fma_f32 v20, v24, v12, v25
	v_mul_f32_e32 v21, v7, v13
	v_mul_f32_e32 v2, v6, v14
	v_add_f32_e32 v21, v21, v20
	v_add_f32_e32 v2, v2, v21
	v_fma_f32 v20, v24, v13, v25
	v_mul_f32_e32 v21, v7, v14
	v_mul_f32_e32 v3, v6, v15
	v_add_f32_e32 v21, v21, v20
	v_add_f32_e32 v3, v3, v21
	v_fma_f32 v20, v24, v14, v25
	v_mul_f32_e32 v21, v7, v15
	v_mul_f32_e32 v28, v6, v16
	v_add_f32_e32 v21, v21, v20
	v_add_f32_e32 v28, v28, v21
	v_fma_f32 v20, v24, v15, v25
	v_mul_f32_e32 v21, v7, v16
	v_mul_f32_e32 v29, v6, v17
	v_add_f32_e32 v21, v21, v20
	v_add_f32_e32 v29, v29, v21
	v_fma_f32 v20, v24, v16, v25
	v_mul_f32_e32 v21, v7, v17
	v_mul_f32_e32 v30, v6, v18
	v_add_f32_e32 v21, v21, v20
	v_add_f32_e32 v30, v30, v21
	v_fma_f32 v20, v24, v17, v25
	v_mul_f32_e32 v21, v7, v18
	v_mul_f32_e32 v31, v6, v19
	v_add_f32_e32 v21, v21, v20
	v_add_f32_e32 v31, v31, v21
	v_cvt_pk_bf16_f32 v0, v0, v1
	v_cvt_pk_bf16_f32 v1, v2, v3
	v_cvt_pk_bf16_f32 v2, v28, v29
	v_cvt_pk_bf16_f32 v3, v30, v31
	ds_write_b128 v23, v[0:3] offset:41248
	s_waitcnt vmcnt(15)
	v_lshlrev_b32_e32 v10, 16, v50
	v_lshlrev_b32_e32 v19, 16, v54
	v_lshlrev_b32_e32 v11, 16, v40
	v_and_b32_e32 v12, 0xffff0000, v40
	v_lshlrev_b32_e32 v13, 16, v41
	v_and_b32_e32 v14, 0xffff0000, v41
	v_lshlrev_b32_e32 v15, 16, v42
	v_and_b32_e32 v16, 0xffff0000, v42
	v_lshlrev_b32_e32 v17, 16, v43
	v_and_b32_e32 v18, 0xffff0000, v43
	v_cndmask_b32_e64 v10, 0, v10, s[22:23]
	v_cndmask_b32_e64 v19, 0, v19, s[60:61]
	v_fma_f32 v20, v24, v10, v25
	v_mul_f32_e32 v21, v7, v11
	v_mul_f32_e32 v0, v6, v12
	v_add_f32_e32 v21, v21, v20
	v_add_f32_e32 v0, v0, v21
	v_fma_f32 v20, v24, v11, v25
	v_mul_f32_e32 v21, v7, v12
	v_mul_f32_e32 v1, v6, v13
	v_add_f32_e32 v21, v21, v20
	v_add_f32_e32 v1, v1, v21
	v_fma_f32 v20, v24, v12, v25
	v_mul_f32_e32 v21, v7, v13
	v_mul_f32_e32 v2, v6, v14
	v_add_f32_e32 v21, v21, v20
	v_add_f32_e32 v2, v2, v21
	v_fma_f32 v20, v24, v13, v25
	v_mul_f32_e32 v21, v7, v14
	v_mul_f32_e32 v3, v6, v15
	v_add_f32_e32 v21, v21, v20
	v_add_f32_e32 v3, v3, v21
	v_fma_f32 v20, v24, v14, v25
	v_mul_f32_e32 v21, v7, v15
	v_mul_f32_e32 v28, v6, v16
	v_add_f32_e32 v21, v21, v20
	v_add_f32_e32 v28, v28, v21
	v_fma_f32 v20, v24, v15, v25
	v_mul_f32_e32 v21, v7, v16
	v_mul_f32_e32 v29, v6, v17
	v_add_f32_e32 v21, v21, v20
	v_add_f32_e32 v29, v29, v21
	v_fma_f32 v20, v24, v16, v25
	v_mul_f32_e32 v21, v7, v17
	v_mul_f32_e32 v30, v6, v18
	v_add_f32_e32 v21, v21, v20
	v_add_f32_e32 v30, v30, v21
	v_fma_f32 v20, v24, v17, v25
	v_mul_f32_e32 v21, v7, v18
	v_mul_f32_e32 v31, v6, v19
	v_add_f32_e32 v21, v21, v20
	v_add_f32_e32 v31, v31, v21
	v_cvt_pk_bf16_f32 v0, v0, v1
	v_cvt_pk_bf16_f32 v1, v2, v3
	v_cvt_pk_bf16_f32 v2, v28, v29
	v_cvt_pk_bf16_f32 v3, v30, v31
	ds_write_b128 v23, v[0:3] offset:49472
	s_waitcnt vmcnt(12)
	v_lshlrev_b32_e32 v10, 16, v51
	v_lshlrev_b32_e32 v19, 16, v55
	v_lshlrev_b32_e32 v11, 16, v44
	v_and_b32_e32 v12, 0xffff0000, v44
	v_lshlrev_b32_e32 v13, 16, v45
	v_and_b32_e32 v14, 0xffff0000, v45
	v_lshlrev_b32_e32 v15, 16, v46
	v_and_b32_e32 v16, 0xffff0000, v46
	v_lshlrev_b32_e32 v17, 16, v47
	v_and_b32_e32 v18, 0xffff0000, v47
	v_cndmask_b32_e64 v10, 0, v10, s[22:23]
	v_cndmask_b32_e64 v19, 0, v19, s[60:61]
	v_fma_f32 v20, v24, v10, v25
	v_mul_f32_e32 v21, v7, v11
	v_mul_f32_e32 v0, v6, v12
	v_add_f32_e32 v21, v21, v20
	v_add_f32_e32 v0, v0, v21
	v_fma_f32 v20, v24, v11, v25
	v_mul_f32_e32 v21, v7, v12
	v_mul_f32_e32 v1, v6, v13
	v_add_f32_e32 v21, v21, v20
	v_add_f32_e32 v1, v1, v21
	v_fma_f32 v20, v24, v12, v25
	v_mul_f32_e32 v21, v7, v13
	v_mul_f32_e32 v2, v6, v14
	v_add_f32_e32 v21, v21, v20
	v_add_f32_e32 v2, v2, v21
	v_fma_f32 v20, v24, v13, v25
	v_mul_f32_e32 v21, v7, v14
	v_mul_f32_e32 v3, v6, v15
	v_add_f32_e32 v21, v21, v20
	v_add_f32_e32 v3, v3, v21
	v_fma_f32 v20, v24, v14, v25
	v_mul_f32_e32 v21, v7, v15
	v_mul_f32_e32 v28, v6, v16
	v_add_f32_e32 v21, v21, v20
	v_add_f32_e32 v28, v28, v21
	v_fma_f32 v20, v24, v15, v25
	v_mul_f32_e32 v21, v7, v16
	v_mul_f32_e32 v29, v6, v17
	v_add_f32_e32 v21, v21, v20
	v_add_f32_e32 v29, v29, v21
	v_fma_f32 v20, v24, v16, v25
	v_mul_f32_e32 v21, v7, v17
	v_mul_f32_e32 v30, v6, v18
	v_add_f32_e32 v21, v21, v20
	v_add_f32_e32 v30, v30, v21
	v_fma_f32 v20, v24, v17, v25
	v_mul_f32_e32 v21, v7, v18
	v_mul_f32_e32 v31, v6, v19
	v_add_f32_e32 v21, v21, v20
	v_add_f32_e32 v31, v31, v21
	v_cvt_pk_bf16_f32 v0, v0, v1
	v_cvt_pk_bf16_f32 v1, v2, v3
	v_cvt_pk_bf16_f32 v2, v28, v29
	v_cvt_pk_bf16_f32 v3, v30, v31
	ds_write_b128 v23, v[0:3] offset:57696
; __device__ __forceinline__ float bf2f(u16 h) { return __uint_as_float(((unsigned)h) << 16); }
; __device__ __forceinline__ unsigned pack2(float a, float b) { unsigned r; asm("v_cvt_pk_bf16_f32 %0, %1, %2" : "=v"(r) : "v"(a), "v"(b)); return r; }
; __device__ __forceinline__ u32x4 conv3x8(const u16* seq, int t8, int Ls, float w0, float w1, float w2, float cb) {
;   u32x4 v = *(const u32x4*)(seq + t8);
;   float z[10];
;   z[0] = t8 > 0 ? bf2f(seq[t8 - 1]) : 0.f;
;   z[1] = __uint_as_float(v.x << 16); z[2] = __uint_as_float(v.x & 0xffff0000u);
;   z[3] = __uint_as_float(v.y << 16); z[4] = __uint_as_float(v.y & 0xffff0000u);
;   z[5] = __uint_as_float(v.z << 16); z[6] = __uint_as_float(v.z & 0xffff0000u);
;   z[7] = __uint_as_float(v.w << 16); z[8] = __uint_as_float(v.w & 0xffff0000u);
;   z[9] = (t8 + 8 < Ls) ? bf2f(seq[t8 + 8]) : 0.f;
;   float o[8];
; #pragma unroll
;   for (int i = 0; i < 8; i++) o[i] = cb + w0 * z[i] + w1 * z[i + 1] + w2 * z[i + 2];
;   u32x4 r; r.x = pack2(o[0], o[1]); r.y = pack2(o[2], o[3]); r.z = pack2(o[4], o[5]); r.w = pack2(o[6], o[7]);
;   return r;
; }
; __device__ __forceinline__ void hyena_task(const Params& p, int layer, int c, bool isctx, unsigned char* smem) {
;     ...
;         if (o == 0) *(u32x4*)(YA + b * HY_YS + t8) = conv3x8(ZHT + (size_t)c * TA + rowoff, t8, Ls, w0, w1, w2, cb);
;         *(u32x4*)(GT + b * HY_YS + t8) = conv3x8(ZHT + (size_t)gch * TA + rowoff, t8, Ls, gw0, gw1, gw2, gcb);
.Lhc_gcomp:
	s_waitcnt vmcnt(9)
	v_lshlrev_b32_e32 v10, 16, v96
	v_lshlrev_b32_e32 v19, 16, v100
	v_lshlrev_b32_e32 v11, 16, v56
	v_and_b32_e32 v12, 0xffff0000, v56
	v_lshlrev_b32_e32 v13, 16, v57
	v_and_b32_e32 v14, 0xffff0000, v57
	v_lshlrev_b32_e32 v15, 16, v58
	v_and_b32_e32 v16, 0xffff0000, v58
	v_lshlrev_b32_e32 v17, 16, v59
	v_and_b32_e32 v18, 0xffff0000, v59
	v_cndmask_b32_e64 v10, 0, v10, s[22:23]
	v_cndmask_b32_e64 v19, 0, v19, s[60:61]
	v_fma_f32 v20, v26, v10, v27
	v_mul_f32_e32 v21, v5, v11
	v_mul_f32_e32 v0, v4, v12
	v_add_f32_e32 v21, v21, v20
	v_add_f32_e32 v0, v0, v21
	v_fma_f32 v20, v26, v11, v27
	v_mul_f32_e32 v21, v5, v12
	v_mul_f32_e32 v1, v4, v13
	v_add_f32_e32 v21, v21, v20
	v_add_f32_e32 v1, v1, v21
	v_fma_f32 v20, v26, v12, v27
	v_mul_f32_e32 v21, v5, v13
	v_mul_f32_e32 v2, v4, v14
	v_add_f32_e32 v21, v21, v20
	v_add_f32_e32 v2, v2, v21
	v_fma_f32 v20, v26, v13, v27
	v_mul_f32_e32 v21, v5, v14
	v_mul_f32_e32 v3, v4, v15
	v_add_f32_e32 v21, v21, v20
	v_add_f32_e32 v3, v3, v21
	v_fma_f32 v20, v26, v14, v27
	v_mul_f32_e32 v21, v5, v15
	v_mul_f32_e32 v28, v4, v16
	v_add_f32_e32 v21, v21, v20
	v_add_f32_e32 v28, v28, v21
	v_fma_f32 v20, v26, v15, v27
	v_mul_f32_e32 v21, v5, v16
	v_mul_f32_e32 v29, v4, v17
	v_add_f32_e32 v21, v21, v20
	v_add_f32_e32 v29, v29, v21
	v_fma_f32 v20, v26, v16, v27
	v_mul_f32_e32 v21, v5, v17
	v_mul_f32_e32 v30, v4, v18
	v_add_f32_e32 v21, v21, v20
	v_add_f32_e32 v30, v30, v21
	v_fma_f32 v20, v26, v17, v27
	v_mul_f32_e32 v21, v5, v18
	v_mul_f32_e32 v31, v4, v19
	v_add_f32_e32 v21, v21, v20
	v_add_f32_e32 v31, v31, v21
	v_cvt_pk_bf16_f32 v0, v0, v1
	v_cvt_pk_bf16_f32 v1, v2, v3
	v_cvt_pk_bf16_f32 v2, v28, v29
	v_cvt_pk_bf16_f32 v3, v30, v31
	ds_write_b128 v22, v[0:3]
	s_waitcnt vmcnt(6)
	v_lshlrev_b32_e32 v10, 16, v97
	v_lshlrev_b32_e32 v19, 16, v101
	v_lshlrev_b32_e32 v11, 16, v60
	v_and_b32_e32 v12, 0xffff0000, v60
	v_lshlrev_b32_e32 v13, 16, v61
	v_and_b32_e32 v14, 0xffff0000, v61
	v_lshlrev_b32_e32 v15, 16, v62
	v_and_b32_e32 v16, 0xffff0000, v62
	v_lshlrev_b32_e32 v17, 16, v63
	v_and_b32_e32 v18, 0xffff0000, v63
	v_cndmask_b32_e64 v10, 0, v10, s[22:23]
	v_cndmask_b32_e64 v19, 0, v19, s[60:61]
	v_fma_f32 v20, v26, v10, v27
	v_mul_f32_e32 v21, v5, v11
	v_mul_f32_e32 v0, v4, v12
	v_add_f32_e32 v21, v21, v20
	v_add_f32_e32 v0, v0, v21
	v_fma_f32 v20, v26, v11, v27
	v_mul_f32_e32 v21, v5, v12
	v_mul_f32_e32 v1, v4, v13
	v_add_f32_e32 v21, v21, v20
	v_add_f32_e32 v1, v1, v21
	v_fma_f32 v20, v26, v12, v27
	v_mul_f32_e32 v21, v5, v13
	v_mul_f32_e32 v2, v4, v14
	v_add_f32_e32 v21, v21, v20
	v_add_f32_e32 v2, v2, v21
	v_fma_f32 v20, v26, v13, v27
	v_mul_f32_e32 v21, v5, v14
	v_mul_f32_e32 v3, v4, v15
	v_add_f32_e32 v21, v21, v20
	v_add_f32_e32 v3, v3, v21
	v_fma_f32 v20, v26, v14, v27
	v_mul_f32_e32 v21, v5, v15
	v_mul_f32_e32 v28, v4, v16
	v_add_f32_e32 v21, v21, v20
	v_add_f32_e32 v28, v28, v21
	v_fma_f32 v20, v26, v15, v27
	v_mul_f32_e32 v21, v5, v16
	v_mul_f32_e32 v29, v4, v17
	v_add_f32_e32 v21, v21, v20
	v_add_f32_e32 v29, v29, v21
	v_fma_f32 v20, v26, v16, v27
	v_mul_f32_e32 v21, v5, v17
	v_mul_f32_e32 v30, v4, v18
	v_add_f32_e32 v21, v21, v20
	v_add_f32_e32 v30, v30, v21
	v_fma_f32 v20, v26, v17, v27
	v_mul_f32_e32 v21, v5, v18
	v_mul_f32_e32 v31, v4, v19
	v_add_f32_e32 v21, v21, v20
	v_add_f32_e32 v31, v31, v21
	v_cvt_pk_bf16_f32 v0, v0, v1
	v_cvt_pk_bf16_f32 v1, v2, v3
	v_cvt_pk_bf16_f32 v2, v28, v29
	v_cvt_pk_bf16_f32 v3, v30, v31
	ds_write_b128 v22, v[0:3] offset:8224
	s_waitcnt vmcnt(3)
	v_lshlrev_b32_e32 v10, 16, v98
	v_lshlrev_b32_e32 v19, 16, v102
	v_lshlrev_b32_e32 v11, 16, v88
	v_and_b32_e32 v12, 0xffff0000, v88
	v_lshlrev_b32_e32 v13, 16, v89
	v_and_b32_e32 v14, 0xffff0000, v89
	v_lshlrev_b32_e32 v15, 16, v90
	v_and_b32_e32 v16, 0xffff0000, v90
	v_lshlrev_b32_e32 v17, 16, v91
	v_and_b32_e32 v18, 0xffff0000, v91
	v_cndmask_b32_e64 v10, 0, v10, s[22:23]
	v_cndmask_b32_e64 v19, 0, v19, s[60:61]
	v_fma_f32 v20, v26, v10, v27
	v_mul_f32_e32 v21, v5, v11
	v_mul_f32_e32 v0, v4, v12
	v_add_f32_e32 v21, v21, v20
	v_add_f32_e32 v0, v0, v21
	v_fma_f32 v20, v26, v11, v27
	v_mul_f32_e32 v21, v5, v12
	v_mul_f32_e32 v1, v4, v13
	v_add_f32_e32 v21, v21, v20
	v_add_f32_e32 v1, v1, v21
	v_fma_f32 v20, v26, v12, v27
	v_mul_f32_e32 v21, v5, v13
	v_mul_f32_e32 v2, v4, v14
	v_add_f32_e32 v21, v21, v20
	v_add_f32_e32 v2, v2, v21
	v_fma_f32 v20, v26, v13, v27
	v_mul_f32_e32 v21, v5, v14
	v_mul_f32_e32 v3, v4, v15
	v_add_f32_e32 v21, v21, v20
	v_add_f32_e32 v3, v3, v21
	v_fma_f32 v20, v26, v14, v27
	v_mul_f32_e32 v21, v5, v15
	v_mul_f32_e32 v28, v4, v16
	v_add_f32_e32 v21, v21, v20
	v_add_f32_e32 v28, v28, v21
	v_fma_f32 v20, v26, v15, v27
	v_mul_f32_e32 v21, v5, v16
	v_mul_f32_e32 v29, v4, v17
	v_add_f32_e32 v21, v21, v20
	v_add_f32_e32 v29, v29, v21
	v_fma_f32 v20, v26, v16, v27
	v_mul_f32_e32 v21, v5, v17
	v_mul_f32_e32 v30, v4, v18
	v_add_f32_e32 v21, v21, v20
	v_add_f32_e32 v30, v30, v21
	v_fma_f32 v20, v26, v17, v27
	v_mul_f32_e32 v21, v5, v18
	v_mul_f32_e32 v31, v4, v19
	v_add_f32_e32 v21, v21, v20
	v_add_f32_e32 v31, v31, v21
	v_cvt_pk_bf16_f32 v0, v0, v1
	v_cvt_pk_bf16_f32 v1, v2, v3
	v_cvt_pk_bf16_f32 v2, v28, v29
	v_cvt_pk_bf16_f32 v3, v30, v31
	ds_write_b128 v22, v[0:3] offset:16448
	s_waitcnt vmcnt(0)
	v_lshlrev_b32_e32 v10, 16, v99
	v_lshlrev_b32_e32 v19, 16, v103
	v_lshlrev_b32_e32 v11, 16, v92
	v_and_b32_e32 v12, 0xffff0000, v92
	v_lshlrev_b32_e32 v13, 16, v93
	v_and_b32_e32 v14, 0xffff0000, v93
	v_lshlrev_b32_e32 v15, 16, v94
	v_and_b32_e32 v16, 0xffff0000, v94
	v_lshlrev_b32_e32 v17, 16, v95
	v_and_b32_e32 v18, 0xffff0000, v95
	v_cndmask_b32_e64 v10, 0, v10, s[22:23]
	v_cndmask_b32_e64 v19, 0, v19, s[60:61]
	v_fma_f32 v20, v26, v10, v27
	v_mul_f32_e32 v21, v5, v11
	v_mul_f32_e32 v0, v4, v12
	v_add_f32_e32 v21, v21, v20
	v_add_f32_e32 v0, v0, v21
	v_fma_f32 v20, v26, v11, v27
	v_mul_f32_e32 v21, v5, v12
	v_mul_f32_e32 v1, v4, v13
	v_add_f32_e32 v21, v21, v20
	v_add_f32_e32 v1, v1, v21
	v_fma_f32 v20, v26, v12, v27
	v_mul_f32_e32 v21, v5, v13
	v_mul_f32_e32 v2, v4, v14
	v_add_f32_e32 v21, v21, v20
	v_add_f32_e32 v2, v2, v21
	v_fma_f32 v20, v26, v13, v27
	v_mul_f32_e32 v21, v5, v14
	v_mul_f32_e32 v3, v4, v15
	v_add_f32_e32 v21, v21, v20
	v_add_f32_e32 v3, v3, v21
	v_fma_f32 v20, v26, v14, v27
	v_mul_f32_e32 v21, v5, v15
	v_mul_f32_e32 v28, v4, v16
	v_add_f32_e32 v21, v21, v20
	v_add_f32_e32 v28, v28, v21
	v_fma_f32 v20, v26, v15, v27
	v_mul_f32_e32 v21, v5, v16
	v_mul_f32_e32 v29, v4, v17
	v_add_f32_e32 v21, v21, v20
	v_add_f32_e32 v29, v29, v21
	v_fma_f32 v20, v26, v16, v27
	v_mul_f32_e32 v21, v5, v17
	v_mul_f32_e32 v30, v4, v18
	v_add_f32_e32 v21, v21, v20
	v_add_f32_e32 v30, v30, v21
	v_fma_f32 v20, v26, v17, v27
	v_mul_f32_e32 v21, v5, v18
	v_mul_f32_e32 v31, v4, v19
	v_add_f32_e32 v21, v21, v20
	v_add_f32_e32 v31, v31, v21
	v_cvt_pk_bf16_f32 v0, v0, v1
	v_cvt_pk_bf16_f32 v1, v2, v3
	v_cvt_pk_bf16_f32 v2, v28, v29
	v_cvt_pk_bf16_f32 v3, v30, v31
	ds_write_b128 v22, v[0:3] offset:24672
